# unit-loop headers: has_next flags computed with scalar compare/cselect instead of VALU 64-bit compares and cndmask round trips
# speedup vs baseline: 1.0225x; 1.0001x over previous
;     __host__ __device__ bool next(int i, Unit& u) const {
;         const long L = (long)i * G + c; if (L >= nwg) return false;
;         int wgid = (int)L; { const int q = nwg / NXCD, r = nwg % NXCD, xcd = wgid % NXCD, off = wgid / NXCD; wgid = (xcd < r ? xcd * (q + 1) : r * (q + 1) + (xcd - r) * q) + off; }
;         const int nig = WGM * nN, gid = wgid / nig, fm = gid * WGM, gsz = (nM - fm) < WGM ? (nM - fm) : WGM;
;         u.pm = fm + ((wgid % nig) % gsz); u.pn = (wgid % nig) / gsz; return true;
;     }
; template <class Epi, class Sched, bool ALIGN_EPI = false, bool SP2 = false>
; __device__ __forceinline__ void gemm_phase(PG8_LAS unsigned char* lds, const Gemm g, const Sched& S, const Epi& E) {
;     ...
;         const bool has_next = S.next(ui + 1, nxt);
;         const char* nA = has_next ? (const char*)g.A + (size_t)nxt.pm * tstep : cA; const char* nB = has_next ? (const char*)g.Bt + (size_t)nxt.pn * tstep : cB;
.LBB0_348:
	s_add_i32 s79, s79, 1
	s_mul_i32 s0, s79, s73
	s_mul_hi_u32 s1, s79, s83
	s_add_i32 s1, s1, s0
	s_mul_i32 s0, s79, s83
	s_add_u32 s2, s0, s86
	s_addc_u32 s3, s1, s74
	s_cmp_lt_u32 s2, 0xb80
	s_cselect_b64 s[0:1], -1, 0
	s_cbranch_scc0 .LBB0_350
	s_ashr_i32 s3, s2, 31
	s_lshr_b32 s3, s3, 29
	s_add_i32 s3, s2, s3
	s_ashr_i32 s11, s3, 3
	s_and_b32 s3, s3, -8
	s_sub_i32 s2, s2, s3
	s_cmp_lt_i32 s2, 0
	s_movk_i32 s3, 0x171
	s_cselect_b32 s3, s3, 0x170
	s_mul_i32 s2, s2, s3
	s_add_i32 s2, s2, s11
	s_mul_hi_i32 s3, s2, 0xb21642c9
	s_add_i32 s3, s3, s2
	s_lshr_b32 s11, s3, 31
	s_ashr_i32 s3, s3, 7
	s_add_i32 s3, s3, s11
	s_lshl_b32 s11, s3, 3
	s_mulk_i32 s3, 0xb8
	s_sub_i32 s2, s2, s3
	s_lshr_b32 s80, s2, 3
	s_and_b32 s2, s2, 7
	s_add_i32 s81, s11, s2
	s_add_i32 s80, s80, s32
	s_sub_i32 s2, s80, 23
	s_cmp_ge_i32 s80, 23
	s_cselect_b32 s80, s2, s80
.LBB0_350:
	s_not_b64 s[2:3], s[0:1]
	s_andn2_b64 vcc, exec, s[0:1]
	s_mov_b64 s[0:1], s[4:5]
	s_cbranch_vccnz .LBB0_352
	s_ashr_i32 s0, s81, 31
	s_mul_hi_u32 s1, s14, s81
	s_mul_i32 s0, s14, s0
	s_add_i32 s0, s1, s0
	s_mul_i32 s1, s15, s81
	s_add_i32 s1, s0, s1
	s_mul_i32 s0, s14, s81
	s_add_u32 s0, s8, s0
	s_addc_u32 s1, s9, s1

;     __host__ __device__ bool next(int i, Unit& u) const {
;         const long L = (long)i * G + c; if (L >= nwg) return false;
;         int wgid = (int)L; { const int q = nwg / NXCD, r = nwg % NXCD, xcd = wgid % NXCD, off = wgid / NXCD; wgid = (xcd < r ? xcd * (q + 1) : r * (q + 1) + (xcd - r) * q) + off; }
;         const int nig = WGM * nN, gid = wgid / nig, fm = gid * WGM, gsz = (nM - fm) < WGM ? (nM - fm) : WGM;
;         u.pm = fm + ((wgid % nig) % gsz); u.pn = (wgid % nig) / gsz; return true;
.LBB0_700:
	s_add_i32 s44, s44, 1
	s_mul_i32 s0, s44, s51
	s_mul_hi_u32 s1, s44, s83
	s_add_i32 s1, s1, s0
	s_mul_i32 s0, s44, s83
	s_add_u32 s4, s0, s80
	s_addc_u32 s5, s1, s52
	s_cmp_lt_u32 s4, 0x400
	s_cselect_b64 s[0:1], -1, 0
	s_cbranch_scc0 .LBB0_706
	s_ashr_i32 s5, s4, 31
	s_lshr_b32 s5, s5, 29
	s_add_i32 s28, s4, s5
	s_and_b32 s5, s28, -8
	s_sub_i32 s29, s4, s5
	s_cmp_gt_i32 s29, -1
	s_mov_b64 s[4:5], -1
	s_cbranch_scc0 .LBB0_703
	s_lshl_b32 s56, s29, 7
	s_mov_b64 s[4:5], 0

; template <class Epi, class Sched, bool ALIGN_EPI = false, bool SP2 = false>
; __device__ __forceinline__ void gemm_phase(PG8_LAS unsigned char* lds, const Gemm g, const Sched& S, const Epi& E) {
;     ...
;         const bool has_next = S.next(ui + 1, nxt);
;         const char* nA = has_next ? (const char*)g.A + (size_t)nxt.pm * tstep : cA; const char* nB = has_next ? (const char*)g.Bt + (size_t)nxt.pn * tstep : cB;
.LBB0_706:
	s_not_b64 s[4:5], s[0:1]
	s_andn2_b64 vcc, exec, s[0:1]
	s_mov_b64 s[0:1], s[6:7]
	s_cbranch_vccnz .LBB0_708
	s_ashr_i32 s0, s57, 31
	s_mul_hi_u32 s1, s12, s57
	s_mul_i32 s0, s12, s0
	s_add_i32 s0, s1, s0
	s_mul_i32 s1, s13, s57
	s_add_i32 s1, s0, s1
	s_mul_i32 s0, s12, s57
	s_add_u32 s0, s33, s0
	s_addc_u32 s1, s36, s1

;     __host__ __device__ bool next(int i, Unit& u) const {
;         const long L = (long)i * G + c; if (L >= nwg) return false;
;         int wgid = (int)L; { const int q = nwg / NXCD, r = nwg % NXCD, xcd = wgid % NXCD, off = wgid / NXCD; wgid = (xcd < r ? xcd * (q + 1) : r * (q + 1) + (xcd - r) * q) + off; }
;         const int nig = WGM * nN, gid = wgid / nig, fm = gid * WGM, gsz = (nM - fm) < WGM ? (nM - fm) : WGM;
;         u.pm = fm + ((wgid % nig) % gsz); u.pn = (wgid % nig) / gsz; return true;
.LBB0_763:
	s_add_i32 s41, s41, 1
	s_mul_i32 s0, s41, s48
	s_mul_hi_u32 s1, s41, s83
	s_add_i32 s1, s1, s0
	s_mul_i32 s0, s41, s83
	s_add_u32 s2, s0, s80
	s_addc_u32 s3, s1, s49
	s_cmp_lt_u32 s2, 0x400
	s_cselect_b64 s[0:1], -1, 0
	s_cbranch_scc0 .LBB0_769
	s_ashr_i32 s3, s2, 31
	s_lshr_b32 s3, s3, 29
	s_add_i32 s28, s2, s3
	s_and_b32 s3, s28, -8
	s_sub_i32 s29, s2, s3
	s_cmp_gt_i32 s29, -1
	s_mov_b64 s[2:3], -1
	s_cbranch_scc0 .LBB0_766
	s_lshl_b32 s52, s29, 7
	s_mov_b64 s[2:3], 0

; template <class Epi, class Sched, bool ALIGN_EPI = false, bool SP2 = false>
; __device__ __forceinline__ void gemm_phase(PG8_LAS unsigned char* lds, const Gemm g, const Sched& S, const Epi& E) {
;     ...
;         const bool has_next = S.next(ui + 1, nxt);
;         const char* nA = has_next ? (const char*)g.A + (size_t)nxt.pm * tstep : cA; const char* nB = has_next ? (const char*)g.Bt + (size_t)nxt.pn * tstep : cB;
.LBB0_769:
	s_not_b64 s[2:3], s[0:1]
	s_andn2_b64 vcc, exec, s[0:1]
	s_mov_b64 s[0:1], s[10:11]
	s_cbranch_vccnz .LBB0_771
	s_ashr_i32 s0, s53, 31
	s_mul_hi_u32 s1, s6, s53
	s_mul_i32 s0, s6, s0
	s_add_i32 s0, s1, s0
	s_mul_i32 s1, s7, s53
	s_add_i32 s1, s0, s1
	s_mul_i32 s0, s6, s53
	s_add_u32 s0, s8, s0
	s_addc_u32 s1, s9, s1

;     __host__ __device__ bool next(int i, Unit& u) const {
;         const long L = (long)i * G + c; if (L >= nwg) return false;
;         int wgid = (int)L; { const int q = nwg / NXCD, r = nwg % NXCD, xcd = wgid % NXCD, off = wgid / NXCD; wgid = (xcd < r ? xcd * (q + 1) : r * (q + 1) + (xcd - r) * q) + off; }
;         const int nig = WGM * nN, gid = wgid / nig, fm = gid * WGM, gsz = (nM - fm) < WGM ? (nM - fm) : WGM;
;         u.pm = fm + ((wgid % nig) % gsz); u.pn = (wgid % nig) / gsz; return true;
.LBB0_828:
	s_add_i32 s43, s43, 1
	s_mul_i32 s0, s43, s50
	s_mul_hi_u32 s1, s43, s83
	s_add_i32 s1, s1, s0
	s_mul_i32 s0, s43, s83
	s_add_u32 s4, s0, s80
	s_addc_u32 s5, s1, s51
	s_cmp_lt_u32 s4, 0x400
	s_cselect_b64 s[0:1], -1, 0
	s_cbranch_scc0 .LBB0_834
	s_ashr_i32 s5, s4, 31
	s_lshr_b32 s5, s5, 29
	s_add_i32 s30, s4, s5
	s_and_b32 s5, s30, -8
	s_sub_i32 s31, s4, s5
	s_cmp_gt_i32 s31, -1
	s_mov_b64 s[4:5], -1
	s_cbranch_scc0 .LBB0_831
	s_lshl_b32 s54, s31, 7
	s_mov_b64 s[4:5], 0

; template <class Epi, class Sched, bool ALIGN_EPI = false, bool SP2 = false>
; __device__ __forceinline__ void gemm_phase(PG8_LAS unsigned char* lds, const Gemm g, const Sched& S, const Epi& E) {
;     ...
;         const bool has_next = S.next(ui + 1, nxt);
;         const char* nA = has_next ? (const char*)g.A + (size_t)nxt.pm * tstep : cA; const char* nB = has_next ? (const char*)g.Bt + (size_t)nxt.pn * tstep : cB;
.LBB0_834:
	s_not_b64 s[4:5], s[0:1]
	s_andn2_b64 vcc, exec, s[0:1]
	s_mov_b64 s[0:1], s[10:11]
	s_cbranch_vccnz .LBB0_836
	s_ashr_i32 s0, s55, 31
	s_mul_hi_u32 s1, s12, s55
	s_mul_i32 s0, s12, s0
	s_add_i32 s0, s1, s0
	s_mul_i32 s1, s13, s55
	s_add_i32 s1, s0, s1
	s_mul_i32 s0, s12, s55
	s_add_u32 s0, s8, s0
	s_addc_u32 s1, s9, s1

;     __host__ __device__ bool next(int i, Unit& u) const {
;         const long L = (long)i * G + c; if (L >= nwg) return false;
;         int wgid = (int)L; { const int q = nwg / NXCD, r = nwg % NXCD, xcd = wgid % NXCD, off = wgid / NXCD; wgid = (xcd < r ? xcd * (q + 1) : r * (q + 1) + (xcd - r) * q) + off; }
;         const int nig = WGM * nN, gid = wgid / nig, fm = gid * WGM, gsz = (nM - fm) < WGM ? (nM - fm) : WGM;
;         u.pm = fm + ((wgid % nig) % gsz); u.pn = (wgid % nig) / gsz; return true;
.LBB0_891:
	s_add_i32 s42, s42, 1
	s_mul_i32 s0, s42, s49
	s_mul_hi_u32 s1, s42, s83
	s_add_i32 s1, s1, s0
	s_mul_i32 s0, s42, s83
	s_add_u32 s2, s0, s80
	s_addc_u32 s3, s1, s50
	s_cmp_lt_u32 s2, 0x400
	s_cselect_b64 s[0:1], -1, 0
	s_cbranch_scc0 .LBB0_897
	s_ashr_i32 s3, s2, 31
	s_lshr_b32 s3, s3, 29
	s_add_i32 s26, s2, s3
	s_and_b32 s3, s26, -8
	s_sub_i32 s27, s2, s3
	s_cmp_gt_i32 s27, -1
	s_mov_b64 s[2:3], -1
	s_cbranch_scc0 .LBB0_894
	s_lshl_b32 s54, s27, 7
	s_mov_b64 s[2:3], 0

; template <class Epi, class Sched, bool ALIGN_EPI = false, bool SP2 = false>
; __device__ __forceinline__ void gemm_phase(PG8_LAS unsigned char* lds, const Gemm g, const Sched& S, const Epi& E) {
;     ...
;         const bool has_next = S.next(ui + 1, nxt);
;         const char* nA = has_next ? (const char*)g.A + (size_t)nxt.pm * tstep : cA; const char* nB = has_next ? (const char*)g.Bt + (size_t)nxt.pn * tstep : cB;
.LBB0_897:
	s_not_b64 s[2:3], s[0:1]
	s_andn2_b64 vcc, exec, s[0:1]
	s_mov_b64 s[0:1], s[4:5]
	s_cbranch_vccnz .LBB0_899
	s_ashr_i32 s0, s55, 31
	s_mul_hi_u32 s1, s10, s55
	s_mul_i32 s0, s10, s0
	s_add_i32 s0, s1, s0
	s_mul_i32 s1, s11, s55
	s_add_i32 s1, s0, s1
	s_mul_i32 s0, s10, s55
	s_add_u32 s0, s33, s0
	s_addc_u32 s1, s34, s1

;     __host__ __device__ bool next(int i, Unit& u) const {
;         const long L = (long)i * G + c; if (L >= nwg) return false;
;         int wgid = (int)L; { const int q = nwg / NXCD, r = nwg % NXCD, xcd = wgid % NXCD, off = wgid / NXCD; wgid = (xcd < r ? xcd * (q + 1) : r * (q + 1) + (xcd - r) * q) + off; }
;         const int nig = WGM * nN, gid = wgid / nig, fm = gid * WGM, gsz = (nM - fm) < WGM ? (nM - fm) : WGM;
;         u.pm = fm + ((wgid % nig) % gsz); u.pn = (wgid % nig) / gsz; return true;
;     }
; template <class Epi, class Sched, bool ALIGN_EPI = false, bool SP2 = false>
; __device__ __forceinline__ void gemm_phase(PG8_LAS unsigned char* lds, const Gemm g, const Sched& S, const Epi& E) {
;     ...
;         const bool has_next = S.next(ui + 1, nxt);
;         const char* nA = has_next ? (const char*)g.A + (size_t)nxt.pm * tstep : cA; const char* nB = has_next ? (const char*)g.Bt + (size_t)nxt.pn * tstep : cB;
.LBB0_1002:
	s_add_i32 s41, s41, 1
	s_mul_i32 s0, s41, s49
	s_mul_hi_u32 s1, s41, s83
	s_add_i32 s1, s1, s0
	s_mul_i32 s0, s41, s83
	s_add_u32 s2, s0, s80
	s_addc_u32 s3, s1, s50
	s_cmp_lt_u32 s2, 0x300
	s_cselect_b64 s[0:1], -1, 0
	s_cbranch_scc0 .LBB0_1004
	s_ashr_i32 s3, s2, 31
	s_lshr_b32 s3, s3, 29
	s_add_i32 s3, s2, s3
	s_ashr_i32 s11, s3, 3
	s_and_b32 s3, s3, -8
	s_sub_i32 s2, s2, s3
	s_cmp_lt_i32 s2, 0
	s_cselect_b32 s3, s51, 0x60
	s_mul_i32 s2, s2, s3
	s_add_i32 s2, s2, s11
	s_mul_hi_i32 s3, s2, 0x2aaaaaab
	s_lshr_b32 s11, s3, 31
	s_ashr_i32 s3, s3, 3
	s_add_i32 s3, s3, s11
	s_lshl_b32 s11, s3, 3
	s_mul_i32 s3, s3, 48
	s_sub_i32 s2, s2, s3
	s_lshr_b32 s33, s2, 3
	s_and_b32 s2, s2, 7
	s_add_i32 s55, s11, s2
.LBB0_1004:
	s_not_b64 s[2:3], s[0:1]
	s_andn2_b64 vcc, exec, s[0:1]
	s_mov_b64 s[0:1], s[4:5]
	s_cbranch_vccnz .LBB0_1006
	s_ashr_i32 s0, s55, 31
	s_mul_hi_u32 s1, s14, s55
	s_mul_i32 s0, s14, s0
	s_add_i32 s0, s1, s0
	s_mul_i32 s1, s15, s55
	s_add_i32 s1, s0, s1
	s_mul_i32 s0, s14, s55
	s_add_u32 s0, s30, s0
	s_addc_u32 s1, s31, s1

;     __host__ __device__ bool next(int i, Unit& u) const {
;         const long L = (long)i * G + c; if (L >= nwg) return false;
;         int wgid = (int)L; { const int q = nwg / NXCD, r = nwg % NXCD, xcd = wgid % NXCD, off = wgid / NXCD; wgid = (xcd < r ? xcd * (q + 1) : r * (q + 1) + (xcd - r) * q) + off; }
;         const int nig = WGM * nN, gid = wgid / nig, fm = gid * WGM, gsz = (nM - fm) < WGM ? (nM - fm) : WGM;
;         u.pm = fm + ((wgid % nig) % gsz); u.pn = (wgid % nig) / gsz; return true;
.LBB0_1299:
	s_add_i32 s39, s39, 1
	s_mul_i32 s0, s39, s51
	s_mul_hi_u32 s1, s39, s83
	s_add_i32 s1, s1, s0
	s_mul_i32 s0, s39, s83
	s_add_u32 s2, s0, s80
	s_addc_u32 s3, s1, s28
	s_cmp_lt_u32 s2, 0x200
	s_cselect_b64 s[0:1], -1, 0
	s_cbranch_scc0 .LBB0_1305
	s_ashr_i32 s3, s2, 31
	s_lshr_b32 s3, s3, 29
	s_add_i32 s18, s2, s3
	s_and_b32 s3, s18, -8
	s_sub_i32 s19, s2, s3
	s_cmp_gt_i32 s19, -1
	s_mov_b64 s[2:3], -1
	s_cbranch_scc0 .LBB0_1302
	s_lshl_b32 s22, s19, 6
	s_mov_b64 s[2:3], 0

; template <class Epi, class Sched, bool ALIGN_EPI = false, bool SP2 = false>
; __device__ __forceinline__ void gemm_phase(PG8_LAS unsigned char* lds, const Gemm g, const Sched& S, const Epi& E) {
;     ...
;         const bool has_next = S.next(ui + 1, nxt);
;         const char* nA = has_next ? (const char*)g.A + (size_t)nxt.pm * tstep : cA; const char* nB = has_next ? (const char*)g.Bt + (size_t)nxt.pn * tstep : cB;
.LBB0_1305:
	s_not_b64 s[2:3], s[0:1]
	s_andn2_b64 vcc, exec, s[0:1]
	s_mov_b64 s[0:1], s[20:21]
	s_cbranch_vccnz .LBB0_1307
	s_ashr_i32 s0, s55, 31
	s_mul_hi_u32 s1, s8, s55
	s_mul_i32 s0, s8, s0
	s_add_i32 s0, s1, s0
	s_mul_i32 s1, s9, s55
	s_add_i32 s1, s0, s1
	s_mul_i32 s0, s8, s55
	s_add_u32 s0, s29, s0
	s_addc_u32 s1, s30, s1

;     __host__ __device__ bool next(int i, Unit& u) const {
;         const long L = (long)i * G + c; if (L >= nwg) return false;
;         int wgid = (int)L; { const int q = nwg / NXCD, r = nwg % NXCD, xcd = wgid % NXCD, off = wgid / NXCD; wgid = (xcd < r ? xcd * (q + 1) : r * (q + 1) + (xcd - r) * q) + off; }
;         const int nig = WGM * nN, gid = wgid / nig, fm = gid * WGM, gsz = (nM - fm) < WGM ? (nM - fm) : WGM;
;         u.pm = fm + ((wgid % nig) % gsz); u.pn = (wgid % nig) / gsz; return true;
.LBB0_1385:
	s_add_i32 s35, s35, 1
	s_mul_i32 s0, s35, s43
	s_mul_hi_u32 s1, s35, s83
	s_add_i32 s1, s1, s0
	s_mul_i32 s0, s35, s83
	s_add_u32 s2, s0, s80
	s_addc_u32 s3, s1, s24
	s_cmp_lt_u32 s2, 0x200
	s_cselect_b64 s[0:1], -1, 0
	s_cbranch_scc0 .LBB0_1391
	s_ashr_i32 s3, s2, 31
	s_lshr_b32 s3, s3, 29
	s_add_i32 s18, s2, s3
	s_and_b32 s3, s18, -8
	s_sub_i32 s19, s2, s3
	s_cmp_gt_i32 s19, -1
	s_mov_b64 s[2:3], -1
	s_cbranch_scc0 .LBB0_1388
	s_lshl_b32 s47, s19, 6
	s_mov_b64 s[2:3], 0

; template <class Epi, class Sched, bool ALIGN_EPI = false, bool SP2 = false>
; __device__ __forceinline__ void gemm_phase(PG8_LAS unsigned char* lds, const Gemm g, const Sched& S, const Epi& E) {
;     ...
;         const bool has_next = S.next(ui + 1, nxt);
;         const char* nA = has_next ? (const char*)g.A + (size_t)nxt.pm * tstep : cA; const char* nB = has_next ? (const char*)g.Bt + (size_t)nxt.pn * tstep : cB;
.LBB0_1391:
	s_not_b64 s[2:3], s[0:1]
	s_andn2_b64 vcc, exec, s[0:1]
	s_mov_b64 s[0:1], s[20:21]
	s_cbranch_vccnz .LBB0_1393
	s_ashr_i32 s0, s48, 31
	s_mul_hi_u32 s1, s8, s48
	s_mul_i32 s0, s8, s0
	s_add_i32 s0, s1, s0
	s_mul_i32 s1, s9, s48
	s_add_i32 s1, s0, s1
	s_mul_i32 s0, s8, s48
	s_add_u32 s0, s25, s0
	s_addc_u32 s1, s26, s1
